# v74 + attention: K/V tile double buffered in LDS, one barrier per tile instead of two
# speedup vs baseline: 1.0117x; 1.0117x over previous
.LBB0_336:
	s_add_i32 s17, s72, 1
	s_cmp_ge_u32 s17, s11
	s_waitcnt vmcnt(0)
	ds_write_b128 v193, v[164:167]
	ds_write_b128 v193, v[160:163] offset:9216
	s_waitcnt lgkmcnt(0)
	s_barrier
	s_cbranch_scc1 .LBB0_342
	s_cmp_gt_u32 s72, 2
	s_mov_b64 s[70:71], -1
	s_cbranch_scc0 .LBB0_339
	s_add_i32 s0, s16, s12
	s_ashr_i32 s1, s0, 31
	s_add_u32 s0, s13, s0
	s_addc_u32 s1, s14, s1
	s_mov_b64 s[70:71], 0

.LBB0_350:
	v_xor_b32_e32 v193, 0x8000, v193
	v_xor_b32_e32 v194, 0x8000, v194
	v_xor_b32_e32 v195, 0x8000, v195
	s_add_i32 s12, s12, 64
	s_cmp_eq_u32 s11, s17
	s_cbranch_scc1 .LBB0_330
	s_mov_b32 s72, s17
	s_branch .LBB0_336
